# GEMM K-loop: second-group B fragment reads issued between the first MFMAs
# speedup vs baseline: 1.0077x; 1.0077x over previous
.LBB0_246:
	s_add_i32 s10, s7, 0xffffa000
	s_cmp_lg_u32 s7, 0
	s_cselect_b32 s12, s10, 0xc000
	v_add_u32_e32 v131, s7, v150
	s_waitcnt vmcnt(6)
	s_barrier
	v_add_u32_e32 v133, s7, v149
	ds_read_b128 v[154:157], v131 offset:0
	ds_read_b128 v[158:161], v131 offset:0x400
	ds_read_b128 v[162:165], v131 offset:0x800
	ds_read_b128 v[166:169], v131 offset:0xc00
	v_add_u32_e32 v131, s12, v147
	ds_read_b128 v[170:173], v133 offset:0
	ds_read_b128 v[174:177], v133 offset:0x400
	ds_read_b128 v[178:181], v133 offset:0x800
	ds_read_b128 v[200:203], v133 offset:0xc00
	s_add_u32 s10, s8, s50
	s_addc_u32 s11, s9, s51
	v_readfirstlane_b32 s13, v131
	s_add_u32 s64, s5, s100
	s_addc_u32 s65, s6, 0
	s_sub_i32 s68, s13, s12
	s_lshr_b32 s68, s68, 1
	s_add_i32 s68, s68, s12
	s_addk_i32 s68, 0x4000
	s_mov_b32 m0, s13
	s_nop 0
	global_load_lds_dwordx4 v0, s[10:11]
	s_add_u32 m0, s13, 0x400
	s_nop 0
	global_load_lds_dwordx4 v130, s[10:11]
	s_waitcnt lgkmcnt(0)
	s_nop 0
	v_mfma_f32_16x16x32_bf16 v[126:129], v[154:157], v[170:173], v[126:129]
	ds_read_b128 v[204:207], v133 offset:0x1000
	v_mfma_f32_16x16x32_bf16 v[122:125], v[154:157], v[174:177], v[122:125]
	ds_read_b128 v[208:211], v133 offset:0x1400
	v_mfma_f32_16x16x32_bf16 v[118:121], v[154:157], v[178:181], v[118:121]
	ds_read_b128 v[212:215], v133 offset:0x1800
	v_mfma_f32_16x16x32_bf16 v[114:117], v[154:157], v[200:203], v[114:117]
	ds_read_b128 v[216:219], v133 offset:0x1c00
	v_mfma_f32_16x16x32_bf16 v[110:113], v[158:161], v[170:173], v[110:113]
	v_mfma_f32_16x16x32_bf16 v[102:105], v[158:161], v[174:177], v[102:105]
	s_add_u32 m0, s13, 0x800
	s_nop 0
	global_load_lds_dwordx4 v132, s[10:11]
	v_mfma_f32_16x16x32_bf16 v[94:97], v[158:161], v[178:181], v[94:97]
	v_mfma_f32_16x16x32_bf16 v[86:89], v[158:161], v[200:203], v[86:89]
	v_mfma_f32_16x16x32_bf16 v[78:81], v[162:165], v[170:173], v[78:81]
	v_mfma_f32_16x16x32_bf16 v[70:73], v[162:165], v[174:177], v[70:73]
	v_mfma_f32_16x16x32_bf16 v[62:65], v[162:165], v[178:181], v[62:65]
	v_mfma_f32_16x16x32_bf16 v[54:57], v[162:165], v[200:203], v[54:57]
	s_add_u32 m0, s13, 0xc00
	s_nop 0
	global_load_lds_dwordx4 v136, s[10:11]
	v_mfma_f32_16x16x32_bf16 v[46:49], v[166:169], v[170:173], v[46:49]
	v_mfma_f32_16x16x32_bf16 v[38:41], v[166:169], v[174:177], v[38:41]
	v_mfma_f32_16x16x32_bf16 v[30:33], v[166:169], v[178:181], v[30:33]
	v_mfma_f32_16x16x32_bf16 v[22:25], v[166:169], v[200:203], v[22:25]
	s_mov_b32 m0, s68
	s_nop 0
	global_load_lds_dwordx4 v138, s[64:65]
	s_waitcnt lgkmcnt(0)
	s_nop 0
	v_mfma_f32_16x16x32_bf16 v[106:109], v[154:157], v[204:207], v[106:109]
	v_mfma_f32_16x16x32_bf16 v[98:101], v[154:157], v[208:211], v[98:101]
	v_mfma_f32_16x16x32_bf16 v[90:93], v[154:157], v[212:215], v[90:93]
	v_mfma_f32_16x16x32_bf16 v[82:85], v[154:157], v[216:219], v[82:85]
	v_mfma_f32_16x16x32_bf16 v[74:77], v[158:161], v[204:207], v[74:77]
	v_mfma_f32_16x16x32_bf16 v[66:69], v[158:161], v[208:211], v[66:69]
	s_add_u32 m0, s68, 0x400
	s_nop 0
	global_load_lds_dwordx4 v140, s[64:65]
	v_mfma_f32_16x16x32_bf16 v[58:61], v[158:161], v[212:215], v[58:61]
	v_mfma_f32_16x16x32_bf16 v[50:53], v[158:161], v[216:219], v[50:53]
	v_mfma_f32_16x16x32_bf16 v[42:45], v[162:165], v[204:207], v[42:45]
	v_mfma_f32_16x16x32_bf16 v[34:37], v[162:165], v[208:211], v[34:37]
	v_mfma_f32_16x16x32_bf16 v[26:29], v[162:165], v[212:215], v[26:29]
	v_mfma_f32_16x16x32_bf16 v[18:21], v[162:165], v[216:219], v[18:21]
	v_mfma_f32_16x16x32_bf16 v[14:17], v[166:169], v[204:207], v[14:17]
	v_mfma_f32_16x16x32_bf16 v[10:13], v[166:169], v[208:211], v[10:13]
	v_mfma_f32_16x16x32_bf16 v[6:9], v[166:169], v[212:215], v[6:9]
	v_mfma_f32_16x16x32_bf16 v[2:5], v[166:169], v[216:219], v[2:5]
	s_add_i32 s10, s7, 0x6000
	s_cmpk_lg_u32 s7, 0xc000
	s_cselect_b32 s7, s10, 0
	s_addk_i32 s100, 0x400
	s_add_u32 s50, s50, s60
	s_addc_u32 s51, s51, 0
	s_cmpk_lg_i32 s100, 0x7800
	s_cbranch_scc1 .LBB0_246
	s_waitcnt vmcnt(6)
	s_barrier
	v_add_u32_e32 v0, s7, v150
	v_add_u32_e32 v140, s7, v149
	ds_read_b128 v[130:133], v0 offset:0
	ds_read_b128 v[136:139], v0 offset:0x400
	ds_read_b128 v[154:157], v0 offset:0x800
	ds_read_b128 v[158:161], v0 offset:0xc00
	ds_read_b128 v[162:165], v140 offset:0
	ds_read_b128 v[166:169], v140 offset:0x400
	ds_read_b128 v[170:173], v140 offset:0x800
	ds_read_b128 v[174:177], v140 offset:0xc00
	ds_read_b128 v[178:181], v140 offset:0x1000
	ds_read_b128 v[200:203], v140 offset:0x1400
	ds_read_b128 v[204:207], v140 offset:0x1800
	ds_read_b128 v[208:211], v140 offset:0x1c00
	s_lshl_b32 s49, s4, 8
	s_waitcnt lgkmcnt(4)
	s_nop 0
	v_mfma_f32_16x16x32_bf16 v[126:129], v[130:133], v[162:165], v[126:129]
	v_mfma_f32_16x16x32_bf16 v[118:121], v[130:133], v[170:173], v[118:121]
	v_mfma_f32_16x16x32_bf16 v[114:117], v[130:133], v[174:177], v[114:117]
	v_mfma_f32_16x16x32_bf16 v[110:113], v[136:139], v[162:165], v[110:113]
	v_mfma_f32_16x16x32_bf16 v[102:105], v[136:139], v[166:169], v[102:105]
	v_mfma_f32_16x16x32_bf16 v[94:97], v[136:139], v[170:173], v[94:97]
	v_mfma_f32_16x16x32_bf16 v[86:89], v[136:139], v[174:177], v[86:89]
	v_mfma_f32_16x16x32_bf16 v[70:73], v[154:157], v[166:169], v[70:73]
	v_mfma_f32_16x16x32_bf16 v[62:65], v[154:157], v[170:173], v[62:65]
	v_mfma_f32_16x16x32_bf16 v[54:57], v[154:157], v[174:177], v[54:57]
	v_mfma_f32_16x16x32_bf16 v[46:49], v[158:161], v[162:165], v[46:49]
	v_mfma_f32_16x16x32_bf16 v[38:41], v[158:161], v[166:169], v[38:41]
	v_mfma_f32_16x16x32_bf16 v[30:33], v[158:161], v[170:173], v[30:33]
	v_mfma_f32_16x16x32_bf16 v[22:25], v[158:161], v[174:177], v[22:25]
	v_mfma_f32_16x16x32_bf16 v[212:215], v[130:133], v[166:169], v[122:125]
	v_mfma_f32_16x16x32_bf16 v[216:219], v[154:157], v[162:165], v[78:81]
	s_waitcnt lgkmcnt(0)
	s_nop 0
	v_mfma_f32_16x16x32_bf16 v[174:177], v[136:139], v[178:181], v[74:77]
	v_mfma_f32_16x16x32_bf16 v[220:223], v[136:139], v[200:203], v[66:69]
	v_mfma_f32_16x16x32_bf16 v[224:227], v[136:139], v[204:207], v[58:61]
	v_mfma_f32_16x16x32_bf16 v[50:53], v[136:139], v[208:211], v[50:53]
	v_mfma_f32_16x16x32_bf16 v[136:139], v[154:157], v[178:181], v[42:45]
	v_mfma_f32_16x16x32_bf16 v[34:37], v[154:157], v[200:203], v[34:37]
	v_mfma_f32_16x16x32_bf16 v[6:9], v[158:161], v[204:207], v[6:9]
	v_mfma_f32_16x16x32_bf16 v[162:165], v[130:133], v[178:181], v[106:109]
	v_mfma_f32_16x16x32_bf16 v[166:169], v[130:133], v[200:203], v[98:101]
	v_mfma_f32_16x16x32_bf16 v[170:173], v[130:133], v[204:207], v[90:93]
	v_mfma_f32_16x16x32_bf16 v[130:133], v[130:133], v[208:211], v[82:85]
	v_mfma_f32_16x16x32_bf16 v[228:231], v[154:157], v[204:207], v[26:29]
	v_mfma_f32_16x16x32_bf16 v[154:157], v[154:157], v[208:211], v[18:21]
	v_mfma_f32_16x16x32_bf16 v[178:181], v[158:161], v[178:181], v[14:17]
	v_mfma_f32_16x16x32_bf16 v[200:203], v[158:161], v[200:203], v[10:13]
	v_mfma_f32_16x16x32_bf16 v[158:161], v[158:161], v[208:211], v[2:5]
	s_waitcnt vmcnt(0)
	s_barrier
	ds_read_b128 v[2:5], v151 offset:0
	ds_read_b128 v[14:17], v151 offset:0x400
	ds_read_b128 v[204:207], v151 offset:0x800
	ds_read_b128 v[208:211], v151 offset:0xc00
	ds_read_b128 v[10:13], v152 offset:0
	ds_read_b128 v[18:21], v152 offset:0x400
	ds_read_b128 v[26:29], v152 offset:0x800
	ds_read_b128 v[42:45], v152 offset:0xc00
	ds_read_b128 v[232:235], v152 offset:0x1000
	ds_read_b128 v[236:239], v152 offset:0x1400
	ds_read_b128 v[240:243], v152 offset:0x1800
	ds_read_b128 v[244:247], v152 offset:0x1c00
	s_nop 0
	s_waitcnt lgkmcnt(4)
	s_nop 0
	v_mfma_f32_16x16x32_bf16 v[122:125], v[2:5], v[10:13], v[126:129]
	v_mfma_f32_16x16x32_bf16 v[106:109], v[2:5], v[18:21], v[212:215]
	v_mfma_f32_16x16x32_bf16 v[90:93], v[2:5], v[26:29], v[118:121]
	v_mfma_f32_16x16x32_bf16 v[74:77], v[2:5], v[42:45], v[114:117]
	v_mfma_f32_16x16x32_bf16 v[126:129], v[14:17], v[10:13], v[110:113]
	v_mfma_f32_16x16x32_bf16 v[110:113], v[14:17], v[18:21], v[102:105]
	v_mfma_f32_16x16x32_bf16 v[94:97], v[14:17], v[26:29], v[94:97]
	v_mfma_f32_16x16x32_bf16 v[78:81], v[14:17], v[42:45], v[86:89]
	v_mfma_f32_16x16x32_bf16 v[114:117], v[204:207], v[10:13], v[216:219]
	v_mfma_f32_16x16x32_bf16 v[98:101], v[204:207], v[18:21], v[70:73]
	v_mfma_f32_16x16x32_bf16 v[82:85], v[204:207], v[26:29], v[62:65]
	v_mfma_f32_16x16x32_bf16 v[66:69], v[204:207], v[42:45], v[54:57]
	v_mfma_f32_16x16x32_bf16 v[118:121], v[208:211], v[10:13], v[46:49]
	v_mfma_f32_16x16x32_bf16 v[102:105], v[208:211], v[18:21], v[38:41]
	v_mfma_f32_16x16x32_bf16 v[86:89], v[208:211], v[26:29], v[30:33]
	v_mfma_f32_16x16x32_bf16 v[70:73], v[208:211], v[42:45], v[22:25]
	s_waitcnt lgkmcnt(0)
	s_nop 0
	v_mfma_f32_16x16x32_bf16 v[58:61], v[2:5], v[232:235], v[162:165]
	v_mfma_f32_16x16x32_bf16 v[42:45], v[2:5], v[236:239], v[166:169]
	v_mfma_f32_16x16x32_bf16 v[26:29], v[2:5], v[240:243], v[170:173]
	v_mfma_f32_16x16x32_bf16 v[10:13], v[2:5], v[244:247], v[130:133]
	v_mfma_f32_16x16x32_bf16 v[62:65], v[14:17], v[232:235], v[174:177]
	v_mfma_f32_16x16x32_bf16 v[46:49], v[14:17], v[236:239], v[220:223]
	v_mfma_f32_16x16x32_bf16 v[30:33], v[14:17], v[240:243], v[224:227]
	v_mfma_f32_16x16x32_bf16 v[14:17], v[14:17], v[244:247], v[50:53]
	v_mfma_f32_16x16x32_bf16 v[50:53], v[204:207], v[232:235], v[136:139]
	v_mfma_f32_16x16x32_bf16 v[34:37], v[204:207], v[236:239], v[34:37]
	v_mfma_f32_16x16x32_bf16 v[18:21], v[204:207], v[240:243], v[228:231]
	v_mfma_f32_16x16x32_bf16 v[2:5], v[204:207], v[244:247], v[154:157]
	v_mfma_f32_16x16x32_bf16 v[54:57], v[208:211], v[232:235], v[178:181]
	v_mfma_f32_16x16x32_bf16 v[38:41], v[208:211], v[236:239], v[200:203]
	v_mfma_f32_16x16x32_bf16 v[22:25], v[208:211], v[240:243], v[6:9]
	v_mfma_f32_16x16x32_bf16 v[6:9], v[208:211], v[244:247], v[158:161]
	v_mov_b32_e32 v136, v134
	s_mov_b64 s[50:51], -1
	s_and_b64 vcc, exec, s[22:23]
	s_barrier
	s_cbranch_vccz .LBB0_264
	s_and_b64 vcc, exec, s[0:1]
	s_cbranch_vccz .LBB0_250
	v_lshrrev_b32_e32 v0, 6, v136
	v_mul_lo_u32 v137, v0, s14
	v_and_b32_e32 v130, 15, v136
	v_and_or_b32 v0, v136, 48, v137
	s_movk_i32 s4, 0x90
	v_mad_u32_u24 v0, v130, s4, v0
	v_cvt_pk_bf16_f32 v130, v122, v123
	v_cvt_pk_bf16_f32 v131, v124, v125
	v_cvt_pk_bf16_f32 v132, v126, v127
	v_cvt_pk_bf16_f32 v133, v128, v129
	s_waitcnt vmcnt(0)
	ds_write_b128 v0, v[130:133]
	v_cvt_pk_bf16_f32 v130, v114, v115
	v_cvt_pk_bf16_f32 v131, v116, v117
	v_cvt_pk_bf16_f32 v132, v118, v119
	v_cvt_pk_bf16_f32 v133, v120, v121
	ds_write_b128 v0, v[130:133] offset:64
	v_cvt_pk_bf16_f32 v130, v106, v107
	v_cvt_pk_bf16_f32 v131, v108, v109
	v_cvt_pk_bf16_f32 v132, v110, v111
	v_cvt_pk_bf16_f32 v133, v112, v113
	ds_write_b128 v0, v[130:133] offset:2304
	v_cvt_pk_bf16_f32 v130, v98, v99
	v_cvt_pk_bf16_f32 v131, v100, v101
	v_cvt_pk_bf16_f32 v132, v102, v103
	v_cvt_pk_bf16_f32 v133, v104, v105
	ds_write_b128 v0, v[130:133] offset:2368
	v_cvt_pk_bf16_f32 v130, v90, v91
	v_cvt_pk_bf16_f32 v131, v92, v93
	v_cvt_pk_bf16_f32 v132, v94, v95
	v_cvt_pk_bf16_f32 v133, v96, v97
	ds_write_b128 v0, v[130:133] offset:4608
	v_cvt_pk_bf16_f32 v130, v82, v83
	v_cvt_pk_bf16_f32 v131, v84, v85
	v_cvt_pk_bf16_f32 v132, v86, v87
	v_cvt_pk_bf16_f32 v133, v88, v89
	ds_write_b128 v0, v[130:133] offset:4672
	v_cvt_pk_bf16_f32 v130, v74, v75
	v_cvt_pk_bf16_f32 v131, v76, v77
	v_cvt_pk_bf16_f32 v132, v78, v79
	v_cvt_pk_bf16_f32 v133, v80, v81
	ds_write_b128 v0, v[130:133] offset:6912
	v_cvt_pk_bf16_f32 v130, v66, v67
	v_cvt_pk_bf16_f32 v131, v68, v69
	v_cvt_pk_bf16_f32 v132, v70, v71
	v_cvt_pk_bf16_f32 v133, v72, v73
	ds_write_b128 v0, v[130:133] offset:6976
	v_cvt_pk_bf16_f32 v130, v58, v59
	v_cvt_pk_bf16_f32 v131, v60, v61
	v_cvt_pk_bf16_f32 v132, v62, v63
	v_cvt_pk_bf16_f32 v133, v64, v65
	ds_write_b128 v0, v[130:133] offset:9216
	v_cvt_pk_bf16_f32 v130, v50, v51
	v_cvt_pk_bf16_f32 v131, v52, v53
	v_cvt_pk_bf16_f32 v132, v54, v55
	v_cvt_pk_bf16_f32 v133, v56, v57
	ds_write_b128 v0, v[130:133] offset:9280
	v_cvt_pk_bf16_f32 v130, v42, v43
	v_cvt_pk_bf16_f32 v131, v44, v45
	v_cvt_pk_bf16_f32 v132, v46, v47
	v_cvt_pk_bf16_f32 v133, v48, v49
	ds_write_b128 v0, v[130:133] offset:11520
	v_cvt_pk_bf16_f32 v130, v34, v35
	v_cvt_pk_bf16_f32 v131, v36, v37
	v_cvt_pk_bf16_f32 v132, v38, v39
	v_cvt_pk_bf16_f32 v133, v40, v41
	ds_write_b128 v0, v[130:133] offset:11584
	v_cvt_pk_bf16_f32 v130, v26, v27
	v_cvt_pk_bf16_f32 v131, v28, v29
	v_cvt_pk_bf16_f32 v132, v30, v31
	v_cvt_pk_bf16_f32 v133, v32, v33
	ds_write_b128 v0, v[130:133] offset:13824
	v_cvt_pk_bf16_f32 v130, v18, v19
	v_cvt_pk_bf16_f32 v131, v20, v21
	v_cvt_pk_bf16_f32 v132, v22, v23
	v_cvt_pk_bf16_f32 v133, v24, v25
	ds_write_b128 v0, v[130:133] offset:13888
	v_cvt_pk_bf16_f32 v130, v10, v11
	v_cvt_pk_bf16_f32 v131, v12, v13
	v_cvt_pk_bf16_f32 v132, v14, v15
	v_cvt_pk_bf16_f32 v133, v16, v17
	ds_write_b128 v0, v[130:133] offset:16128
	v_cvt_pk_bf16_f32 v130, v2, v3
	v_cvt_pk_bf16_f32 v131, v4, v5
	v_cvt_pk_bf16_f32 v132, v6, v7
	v_cvt_pk_bf16_f32 v133, v8, v9
	ds_write_b128 v0, v[130:133] offset:16192
	v_and_b32_e32 v0, 0xffffff80, v136
	v_add_u32_e32 v130, s48, v0
	v_ashrrev_i32_e32 v131, 31, v130
	v_lshlrev_b64 v[130:131], 11, v[130:131]
	v_lshl_add_u64 v[130:131], s[38:39], 0, v[130:131]
	v_and_b32_e32 v0, 64, v136
	v_lshl_add_u64 v[130:131], s[46:47], 1, v[130:131]
	v_lshlrev_b32_e32 v0, 1, v0
	v_lshl_add_u64 v[138:139], v[130:131], 0, v[0:1]
	v_lshlrev_b32_e32 v0, 4, v136
	v_and_b32_e32 v0, 0x70, v0
	v_bfe_u32 v140, v136, 3, 3
	v_or_b32_e32 v130, v137, v0
	s_waitcnt lgkmcnt(0)
	v_mad_u32_u24 v137, v140, s4, v130
	ds_read_b128 v[130:133], v137
	v_lshl_add_u64 v[138:139], v[138:139], 0, v[0:1]
	v_lshlrev_b32_e32 v0, 11, v140
	v_lshl_add_u64 v[140:141], v[138:139], 0, v[0:1]
	s_mov_b64 s[50:51], 0
	s_waitcnt lgkmcnt(0)
	global_store_dwordx4 v[140:141], v[130:133], off
	ds_read_b128 v[130:133], v137 offset:1152
	v_or_b32_e32 v140, 0x4000, v0
	v_mov_b32_e32 v141, v1
	v_lshl_add_u64 v[140:141], v[138:139], 0, v[140:141]
	s_waitcnt lgkmcnt(0)
	global_store_dwordx4 v[140:141], v[130:133], off
	ds_read_b128 v[130:133], v137 offset:2304
	v_or_b32_e32 v140, 0x8000, v0
	v_mov_b32_e32 v141, v1
	v_lshl_add_u64 v[140:141], v[138:139], 0, v[140:141]
	s_waitcnt lgkmcnt(0)
	global_store_dwordx4 v[140:141], v[130:133], off
	ds_read_b128 v[130:133], v137 offset:3456
	v_or_b32_e32 v140, 0xc000, v0
	v_mov_b32_e32 v141, v1
	v_lshl_add_u64 v[140:141], v[138:139], 0, v[140:141]
	s_waitcnt lgkmcnt(0)
	global_store_dwordx4 v[140:141], v[130:133], off
	ds_read_b128 v[130:133], v137 offset:4608
	v_or_b32_e32 v140, 0x10000, v0
	v_mov_b32_e32 v141, v1
	v_lshl_add_u64 v[140:141], v[138:139], 0, v[140:141]
	s_waitcnt lgkmcnt(0)
	global_store_dwordx4 v[140:141], v[130:133], off
	ds_read_b128 v[130:133], v137 offset:5760
	v_or_b32_e32 v140, 0x14000, v0
	v_mov_b32_e32 v141, v1
	v_lshl_add_u64 v[140:141], v[138:139], 0, v[140:141]
	s_waitcnt lgkmcnt(0)
	global_store_dwordx4 v[140:141], v[130:133], off
	ds_read_b128 v[130:133], v137 offset:6912
	v_or_b32_e32 v140, 0x18000, v0
	v_mov_b32_e32 v141, v1
	v_lshl_add_u64 v[140:141], v[138:139], 0, v[140:141]
	s_waitcnt lgkmcnt(0)
	global_store_dwordx4 v[140:141], v[130:133], off
	ds_read_b128 v[130:133], v137 offset:8064
	v_or_b32_e32 v140, 0x1c000, v0
	v_mov_b32_e32 v141, v1
	v_lshl_add_u64 v[140:141], v[138:139], 0, v[140:141]
	s_waitcnt lgkmcnt(0)
	global_store_dwordx4 v[140:141], v[130:133], off
	ds_read_b128 v[130:133], v137 offset:9216
	v_or_b32_e32 v140, 0x20000, v0
	v_mov_b32_e32 v141, v1
	v_lshl_add_u64 v[140:141], v[138:139], 0, v[140:141]
	s_waitcnt lgkmcnt(0)
	global_store_dwordx4 v[140:141], v[130:133], off
	ds_read_b128 v[130:133], v137 offset:10368
	v_or_b32_e32 v140, 0x24000, v0
	v_mov_b32_e32 v141, v1
	v_lshl_add_u64 v[140:141], v[138:139], 0, v[140:141]
	s_waitcnt lgkmcnt(0)
	global_store_dwordx4 v[140:141], v[130:133], off
	ds_read_b128 v[130:133], v137 offset:11520
	v_or_b32_e32 v140, 0x28000, v0
	v_mov_b32_e32 v141, v1
	v_lshl_add_u64 v[140:141], v[138:139], 0, v[140:141]
	s_waitcnt lgkmcnt(0)
	global_store_dwordx4 v[140:141], v[130:133], off
	ds_read_b128 v[130:133], v137 offset:12672
	v_or_b32_e32 v140, 0x2c000, v0
	v_mov_b32_e32 v141, v1
	v_lshl_add_u64 v[140:141], v[138:139], 0, v[140:141]
	s_waitcnt lgkmcnt(0)
	global_store_dwordx4 v[140:141], v[130:133], off
	ds_read_b128 v[130:133], v137 offset:13824
	v_or_b32_e32 v140, 0x30000, v0
	v_mov_b32_e32 v141, v1
	v_lshl_add_u64 v[140:141], v[138:139], 0, v[140:141]
	s_waitcnt lgkmcnt(0)
	global_store_dwordx4 v[140:141], v[130:133], off
	ds_read_b128 v[130:133], v137 offset:14976
	v_or_b32_e32 v140, 0x34000, v0
	v_mov_b32_e32 v141, v1
	v_lshl_add_u64 v[140:141], v[138:139], 0, v[140:141]
	s_waitcnt lgkmcnt(0)
	global_store_dwordx4 v[140:141], v[130:133], off
	ds_read_b128 v[130:133], v137 offset:16128
	v_or_b32_e32 v140, 0x38000, v0
	v_mov_b32_e32 v141, v1
	v_lshl_add_u64 v[140:141], v[138:139], 0, v[140:141]
	v_or_b32_e32 v0, 0x3c000, v0
	s_waitcnt lgkmcnt(0)
	global_store_dwordx4 v[140:141], v[130:133], off
	ds_read_b128 v[130:133], v137 offset:17280
	v_lshl_add_u64 v[138:139], v[138:139], 0, v[0:1]
	s_waitcnt lgkmcnt(0)
	global_store_dwordx4 v[138:139], v[130:133], off
	s_waitcnt lgkmcnt(0)
	s_barrier
